# early acquire-invalidate plus grid-barrier waiters polling the cross-XCD release word directly
# speedup vs baseline: 1.0089x; 1.0029x over previous
.LBB0_137:
	s_or_b64 exec, exec, s[12:13]
	v_cvt_f32_u32_e32 v5, v3
	s_waitcnt vmcnt(0)
	v_readfirstlane_b32 s3, v4
	v_sub_u32_e32 v4, 0, v3
	v_rcp_iflag_f32_e32 v5, v5
	v_add_u32_e32 v6, s3, v2
	v_mul_f32_e32 v5, 0x4f7ffffe, v5
	v_cvt_u32_f32_e32 v5, v5
	v_mul_lo_u32 v2, v4, v5
	v_mul_hi_u32 v2, v5, v2
	v_add_u32_e32 v2, v5, v2
	v_mul_hi_u32 v2, v6, v2
	v_mul_lo_u32 v4, v2, v3
	v_sub_u32_e32 v4, v6, v4
	v_add_u32_e32 v5, 1, v2
	v_cmp_ge_u32_e32 vcc, v4, v3
	s_nop 1
	v_cndmask_b32_e32 v2, v2, v5, vcc
	v_sub_u32_e32 v5, v4, v3
	v_cndmask_b32_e32 v4, v4, v5, vcc
	v_add_u32_e32 v5, 1, v2
	v_cmp_ge_u32_e32 vcc, v4, v3
	v_add_u32_e32 v4, 1, v6
	s_nop 0
	v_cndmask_b32_e32 v2, v2, v5, vcc
	v_mul_lo_u32 v5, v3, v2
	v_add_u32_e32 v3, v5, v3
	v_cmp_ne_u32_e32 vcc, v4, v3
	s_and_saveexec_b64 s[4:5], vcc
	s_xor_b64 s[10:11], exec, s[4:5]
	s_cbranch_execz .LBB0_151
	s_waitcnt lgkmcnt(0)
	buffer_inv sc1
	s_add_u32 s16, s72, 0x7500
	s_addc_u32 s17, s73, 0
	v_mov_b32_e32 v1, 0
	global_load_dword v1, v1, s[16:17] sc1
	s_waitcnt vmcnt(0)
	v_cmp_eq_u32_e32 vcc, v1, v2
	s_and_saveexec_b64 s[12:13], vcc
	s_cbranch_execz .LBB0_150
	s_add_u32 s14, s72, 0x4200
	s_addc_u32 s15, s73, 0
	s_mov_b32 s3, 1
	s_mov_b64 s[18:19], 0
	v_mov_b32_e32 v1, 0
	s_branch .LBB0_141

.LBB0_283:
	s_or_b64 exec, exec, s[10:11]
	v_cvt_f32_u32_e32 v5, v3
	s_waitcnt vmcnt(0)
	v_readfirstlane_b32 s3, v4
	v_sub_u32_e32 v4, 0, v3
	v_rcp_iflag_f32_e32 v5, v5
	v_add_u32_e32 v6, s3, v2
	v_mul_f32_e32 v5, 0x4f7ffffe, v5
	v_cvt_u32_f32_e32 v5, v5
	v_mul_lo_u32 v2, v4, v5
	v_mul_hi_u32 v2, v5, v2
	v_add_u32_e32 v2, v5, v2
	v_mul_hi_u32 v2, v6, v2
	v_mul_lo_u32 v4, v2, v3
	v_sub_u32_e32 v4, v6, v4
	v_add_u32_e32 v5, 1, v2
	v_cmp_ge_u32_e32 vcc, v4, v3
	s_nop 1
	v_cndmask_b32_e32 v2, v2, v5, vcc
	v_sub_u32_e32 v5, v4, v3
	v_cndmask_b32_e32 v4, v4, v5, vcc
	v_add_u32_e32 v5, 1, v2
	v_cmp_ge_u32_e32 vcc, v4, v3
	v_add_u32_e32 v4, 1, v6
	s_nop 0
	v_cndmask_b32_e32 v2, v2, v5, vcc
	v_mul_lo_u32 v5, v3, v2
	v_add_u32_e32 v3, v5, v3
	v_cmp_ne_u32_e32 vcc, v4, v3
	s_and_saveexec_b64 s[4:5], vcc
	s_xor_b64 s[8:9], exec, s[4:5]
	s_cbranch_execz .LBB0_297
	s_waitcnt lgkmcnt(0)
	buffer_inv sc1
	s_add_u32 s16, s72, 0x7500
	s_addc_u32 s17, s73, 0
	v_mov_b32_e32 v1, 0
	global_load_dword v1, v1, s[16:17] sc1
	s_waitcnt vmcnt(0)
	v_cmp_eq_u32_e32 vcc, v1, v2
	s_and_saveexec_b64 s[10:11], vcc
	s_cbranch_execz .LBB0_296
	s_add_u32 s12, s72, 0x4200
	s_addc_u32 s13, s73, 0
	s_mov_b32 s3, 1
	s_mov_b64 s[18:19], 0
	v_mov_b32_e32 v1, 0
	s_branch .LBB0_287

.LBB0_476:
	s_or_b64 exec, exec, s[14:15]
	v_cvt_f32_u32_e32 v5, v3
	s_waitcnt vmcnt(0)
	v_readfirstlane_b32 s3, v4
	v_sub_u32_e32 v4, 0, v3
	v_rcp_iflag_f32_e32 v5, v5
	v_add_u32_e32 v6, s3, v2
	v_mul_f32_e32 v5, 0x4f7ffffe, v5
	v_cvt_u32_f32_e32 v5, v5
	v_mul_lo_u32 v2, v4, v5
	v_mul_hi_u32 v2, v5, v2
	v_add_u32_e32 v2, v5, v2
	v_mul_hi_u32 v2, v6, v2
	v_mul_lo_u32 v4, v2, v3
	v_sub_u32_e32 v4, v6, v4
	v_add_u32_e32 v5, 1, v2
	v_cmp_ge_u32_e32 vcc, v4, v3
	s_nop 1
	v_cndmask_b32_e32 v2, v2, v5, vcc
	v_sub_u32_e32 v5, v4, v3
	v_cndmask_b32_e32 v4, v4, v5, vcc
	v_add_u32_e32 v5, 1, v2
	v_cmp_ge_u32_e32 vcc, v4, v3
	v_add_u32_e32 v4, 1, v6
	s_nop 0
	v_cndmask_b32_e32 v2, v2, v5, vcc
	v_mul_lo_u32 v5, v3, v2
	v_add_u32_e32 v3, v5, v3
	v_cmp_ne_u32_e32 vcc, v4, v3
	s_and_saveexec_b64 s[4:5], vcc
	s_xor_b64 s[12:13], exec, s[4:5]
	s_cbranch_execz .LBB0_490
	s_waitcnt lgkmcnt(0)
	buffer_inv sc1
	s_add_u32 s18, s72, 0x7500
	s_addc_u32 s19, s73, 0
	v_mov_b32_e32 v1, 0
	global_load_dword v1, v1, s[18:19] sc1
	s_waitcnt vmcnt(0)
	v_cmp_eq_u32_e32 vcc, v1, v2
	s_and_saveexec_b64 s[14:15], vcc
	s_cbranch_execz .LBB0_489
	s_add_u32 s16, s72, 0x4200
	s_addc_u32 s17, s73, 0
	s_mov_b32 s3, 1
	s_mov_b64 s[20:21], 0
	v_mov_b32_e32 v1, 0
	s_branch .LBB0_480

.LBB0_738:
	s_or_b64 exec, exec, s[12:13]
	v_cvt_f32_u32_e32 v5, v3
	s_waitcnt vmcnt(0)
	v_readfirstlane_b32 s3, v4
	v_sub_u32_e32 v4, 0, v3
	v_rcp_iflag_f32_e32 v5, v5
	v_add_u32_e32 v6, s3, v2
	v_mul_f32_e32 v5, 0x4f7ffffe, v5
	v_cvt_u32_f32_e32 v5, v5
	v_mul_lo_u32 v2, v4, v5
	v_mul_hi_u32 v2, v5, v2
	v_add_u32_e32 v2, v5, v2
	v_mul_hi_u32 v2, v6, v2
	v_mul_lo_u32 v4, v2, v3
	v_sub_u32_e32 v4, v6, v4
	v_add_u32_e32 v5, 1, v2
	v_cmp_ge_u32_e32 vcc, v4, v3
	s_nop 1
	v_cndmask_b32_e32 v2, v2, v5, vcc
	v_sub_u32_e32 v5, v4, v3
	v_cndmask_b32_e32 v4, v4, v5, vcc
	v_add_u32_e32 v5, 1, v2
	v_cmp_ge_u32_e32 vcc, v4, v3
	v_add_u32_e32 v4, 1, v6
	s_nop 0
	v_cndmask_b32_e32 v2, v2, v5, vcc
	v_mul_lo_u32 v5, v3, v2
	v_add_u32_e32 v3, v5, v3
	v_cmp_ne_u32_e32 vcc, v4, v3
	s_and_saveexec_b64 s[4:5], vcc
	s_xor_b64 s[10:11], exec, s[4:5]
	s_cbranch_execz .LBB0_752
	s_waitcnt lgkmcnt(0)
	buffer_inv sc1
	s_add_u32 s16, s72, 0x7500
	s_addc_u32 s17, s73, 0
	v_mov_b32_e32 v1, 0
	global_load_dword v1, v1, s[16:17] sc1
	s_waitcnt vmcnt(0)
	v_cmp_eq_u32_e32 vcc, v1, v2
	s_and_saveexec_b64 s[12:13], vcc
	s_cbranch_execz .LBB0_751
	s_add_u32 s14, s72, 0x4200
	s_addc_u32 s15, s73, 0
	s_mov_b32 s3, 1
	s_mov_b64 s[20:21], 0
	v_mov_b32_e32 v1, 0
	s_branch .LBB0_742

.LBB0_1612:
	s_or_b64 exec, exec, s[12:13]
	v_cvt_f32_u32_e32 v4, v2
	s_waitcnt vmcnt(0)
	v_readfirstlane_b32 s3, v3
	v_sub_u32_e32 v3, 0, v2
	v_rcp_iflag_f32_e32 v4, v4
	v_add_u32_e32 v5, s3, v1
	v_mul_f32_e32 v4, 0x4f7ffffe, v4
	v_cvt_u32_f32_e32 v4, v4
	v_mul_lo_u32 v1, v3, v4
	v_mul_hi_u32 v1, v4, v1
	v_add_u32_e32 v1, v4, v1
	v_mul_hi_u32 v1, v5, v1
	v_mul_lo_u32 v3, v1, v2
	v_sub_u32_e32 v3, v5, v3
	v_add_u32_e32 v4, 1, v1
	v_cmp_ge_u32_e32 vcc, v3, v2
	s_nop 1
	v_cndmask_b32_e32 v1, v1, v4, vcc
	v_sub_u32_e32 v4, v3, v2
	v_cndmask_b32_e32 v3, v3, v4, vcc
	v_add_u32_e32 v4, 1, v1
	v_cmp_ge_u32_e32 vcc, v3, v2
	v_add_u32_e32 v3, 1, v5
	s_nop 0
	v_cndmask_b32_e32 v1, v1, v4, vcc
	v_mul_lo_u32 v4, v2, v1
	v_add_u32_e32 v2, v4, v2
	v_cmp_ne_u32_e32 vcc, v3, v2
	s_and_saveexec_b64 s[4:5], vcc
	s_xor_b64 s[10:11], exec, s[4:5]
	s_cbranch_execz .LBB0_1626
	s_waitcnt lgkmcnt(0)
	buffer_inv sc1
	s_add_u32 s16, s72, 0x7500
	s_addc_u32 s17, s73, 0
	v_mov_b32_e32 v0, 0
	global_load_dword v0, v0, s[16:17] sc1
	s_waitcnt vmcnt(0)
	v_cmp_eq_u32_e32 vcc, v0, v1
	s_and_saveexec_b64 s[12:13], vcc
	s_cbranch_execz .LBB0_1625
	s_add_u32 s14, s72, 0x4200
	s_addc_u32 s15, s73, 0
	s_mov_b32 s3, 1
	s_mov_b64 s[18:19], 0
	v_mov_b32_e32 v0, 0
	s_branch .LBB0_1616

.LBB0_1722:
	s_or_b64 exec, exec, s[14:15]
	v_cvt_f32_u32_e32 v4, v2
	s_waitcnt vmcnt(0)
	v_readfirstlane_b32 s3, v3
	v_sub_u32_e32 v3, 0, v2
	v_rcp_iflag_f32_e32 v4, v4
	v_add_u32_e32 v5, s3, v1
	v_mul_f32_e32 v4, 0x4f7ffffe, v4
	v_cvt_u32_f32_e32 v4, v4
	v_mul_lo_u32 v1, v3, v4
	v_mul_hi_u32 v1, v4, v1
	v_add_u32_e32 v1, v4, v1
	v_mul_hi_u32 v1, v5, v1
	v_mul_lo_u32 v3, v1, v2
	v_sub_u32_e32 v3, v5, v3
	v_add_u32_e32 v4, 1, v1
	v_cmp_ge_u32_e32 vcc, v3, v2
	s_nop 1
	v_cndmask_b32_e32 v1, v1, v4, vcc
	v_sub_u32_e32 v4, v3, v2
	v_cndmask_b32_e32 v3, v3, v4, vcc
	v_add_u32_e32 v4, 1, v1
	v_cmp_ge_u32_e32 vcc, v3, v2
	v_add_u32_e32 v3, 1, v5
	s_nop 0
	v_cndmask_b32_e32 v1, v1, v4, vcc
	v_mul_lo_u32 v4, v2, v1
	v_add_u32_e32 v2, v4, v2
	v_cmp_ne_u32_e32 vcc, v3, v2
	s_and_saveexec_b64 s[4:5], vcc
	s_xor_b64 s[12:13], exec, s[4:5]
	s_cbranch_execz .LBB0_1736
	s_waitcnt lgkmcnt(0)
	buffer_inv sc1
	s_add_u32 s18, s72, 0x7500
	s_addc_u32 s19, s73, 0
	v_mov_b32_e32 v0, 0
	global_load_dword v0, v0, s[18:19] sc1
	s_waitcnt vmcnt(0)
	v_cmp_eq_u32_e32 vcc, v0, v1
	s_and_saveexec_b64 s[14:15], vcc
	s_cbranch_execz .LBB0_1735
	s_add_u32 s16, s72, 0x4200
	s_addc_u32 s17, s73, 0
	s_mov_b32 s3, 1
	s_mov_b64 s[20:21], 0
	v_mov_b32_e32 v0, 0
	s_branch .LBB0_1726

.LBB0_1847:
	s_or_b64 exec, exec, s[12:13]
	v_cvt_f32_u32_e32 v4, v2
	s_waitcnt vmcnt(0)
	v_readfirstlane_b32 s3, v3
	v_sub_u32_e32 v3, 0, v2
	v_rcp_iflag_f32_e32 v4, v4
	v_add_u32_e32 v5, s3, v1
	v_mul_f32_e32 v4, 0x4f7ffffe, v4
	v_cvt_u32_f32_e32 v4, v4
	v_mul_lo_u32 v1, v3, v4
	v_mul_hi_u32 v1, v4, v1
	v_add_u32_e32 v1, v4, v1
	v_mul_hi_u32 v1, v5, v1
	v_mul_lo_u32 v3, v1, v2
	v_sub_u32_e32 v3, v5, v3
	v_add_u32_e32 v4, 1, v1
	v_cmp_ge_u32_e32 vcc, v3, v2
	s_nop 1
	v_cndmask_b32_e32 v1, v1, v4, vcc
	v_sub_u32_e32 v4, v3, v2
	v_cndmask_b32_e32 v3, v3, v4, vcc
	v_add_u32_e32 v4, 1, v1
	v_cmp_ge_u32_e32 vcc, v3, v2
	v_add_u32_e32 v3, 1, v5
	s_nop 0
	v_cndmask_b32_e32 v1, v1, v4, vcc
	v_mul_lo_u32 v4, v2, v1
	v_add_u32_e32 v2, v4, v2
	v_cmp_ne_u32_e32 vcc, v3, v2
	s_and_saveexec_b64 s[4:5], vcc
	s_xor_b64 s[10:11], exec, s[4:5]
	s_cbranch_execz .LBB0_1861
	s_waitcnt lgkmcnt(0)
	buffer_inv sc1
	s_add_u32 s16, s72, 0x7500
	s_addc_u32 s17, s73, 0
	v_mov_b32_e32 v0, 0
	global_load_dword v0, v0, s[16:17] sc1
	s_waitcnt vmcnt(0)
	v_cmp_eq_u32_e32 vcc, v0, v1
	s_and_saveexec_b64 s[12:13], vcc
	s_cbranch_execz .LBB0_1860
	s_add_u32 s14, s72, 0x4200
	s_addc_u32 s15, s73, 0
	s_mov_b32 s3, 1
	s_mov_b64 s[20:21], 0
	v_mov_b32_e32 v0, 0
	s_branch .LBB0_1851

.LBB0_1963:
	s_or_b64 exec, exec, s[20:21]
	v_cvt_f32_u32_e32 v4, v2
	s_waitcnt vmcnt(0)
	v_readfirstlane_b32 s3, v3
	v_sub_u32_e32 v3, 0, v2
	v_rcp_iflag_f32_e32 v4, v4
	v_add_u32_e32 v5, s3, v1
	v_mul_f32_e32 v4, 0x4f7ffffe, v4
	v_cvt_u32_f32_e32 v4, v4
	v_mul_lo_u32 v1, v3, v4
	v_mul_hi_u32 v1, v4, v1
	v_add_u32_e32 v1, v4, v1
	v_mul_hi_u32 v1, v5, v1
	v_mul_lo_u32 v3, v1, v2
	v_sub_u32_e32 v3, v5, v3
	v_add_u32_e32 v4, 1, v1
	v_cmp_ge_u32_e32 vcc, v3, v2
	s_nop 1
	v_cndmask_b32_e32 v1, v1, v4, vcc
	v_sub_u32_e32 v4, v3, v2
	v_cndmask_b32_e32 v3, v3, v4, vcc
	v_add_u32_e32 v4, 1, v1
	v_cmp_ge_u32_e32 vcc, v3, v2
	v_add_u32_e32 v3, 1, v5
	s_nop 0
	v_cndmask_b32_e32 v1, v1, v4, vcc
	v_mul_lo_u32 v4, v2, v1
	v_add_u32_e32 v2, v4, v2
	v_cmp_ne_u32_e32 vcc, v3, v2
	s_and_saveexec_b64 s[16:17], vcc
	s_xor_b64 s[16:17], exec, s[16:17]
	s_cbranch_execz .LBB0_1977
	s_waitcnt lgkmcnt(0)
	buffer_inv sc1
	s_add_u32 s26, s72, 0x7500
	s_addc_u32 s27, s73, 0
	v_mov_b32_e32 v0, 0
	global_load_dword v0, v0, s[26:27] sc1
	s_waitcnt vmcnt(0)
	v_cmp_eq_u32_e32 vcc, v0, v1
	s_and_saveexec_b64 s[20:21], vcc
	s_cbranch_execz .LBB0_1976
	s_add_u32 s24, s72, 0x4200
	s_addc_u32 s25, s73, 0
	s_mov_b32 s3, 1
	s_mov_b64 s[28:29], 0
	v_mov_b32_e32 v0, 0
	s_branch .LBB0_1967
